# diff P.V section: redundant s_nop removed, per-MFMA lgkmcnt waits merged into one per fragment group
# speedup vs baseline: 1.0047x; 1.0047x over previous
; #define MFMA32(a, b, c) __builtin_amdgcn_mfma_f32_32x32x16_bf16((a), (b), (c), 0, 0, 0)
; #define VFRAG(ptr, off0, STR) ({ const s16x4 lo_ = vtr((ptr) + (off0)); const s16x4 hi_ = vtr((ptr) + (off0) + 8 * (STR)); (bf16x8){lo_[0], lo_[1], lo_[2], lo_[3], hi_[0], hi_[1], hi_[2], hi_[3]}; })
; __device__ __forceinline__ void diff_unit(const Frame& F, int b, int h, int qi, float lam, int dry) {
;     ...
;             float ps = 0.f;
; #pragma unroll
;             for (int r = 0; r < 16; ++r) { s0[r] = __builtin_amdgcn_exp2f(s0[r] * LOG2E - ms); ps += s0[r]; }
;             if (!meta) {
; #pragma unroll
;                 for (int r = 0; r < 16; ++r) { s1[r] = __builtin_amdgcn_exp2f(s1[r] * LOG2E - ms); ps += s1[r]; }
;             }
;             lsum += ps;
;             __builtin_amdgcn_s_setprio(1);
;             { const bf16x8 pf = pack_step(s0, 0);
;               O[0] = MFMA32(vpre0, pf, O[0]); O[1] = MFMA32(vpre1, pf, O[1]); O[2] = MFMA32(vpre2, pf, O[2]); O[3] = MFMA32(vpre3, pf, O[3]); }
;             if (!meta) {
;                 { const bf16x8 pf = pack_step(s0, 1);
;                   O[0] = MFMA32(vprf0, pf, O[0]); O[1] = MFMA32(vprf1, pf, O[1]);
; #pragma unroll
;                   for (int dt = 2; dt < 4; ++dt) { const bf16x8 vf = VFRAG(vb, 16 * DV_STR + 64 * dt, DV_STR); O[dt] = MFMA32(vf, pf, O[dt]); } }
; #pragma unroll
;                 for (int s2 = 0; s2 < 2; ++s2) { const bf16x8 pf = pack_step(s1, s2);
; #pragma unroll
;                     for (int dt = 0; dt < 4; ++dt) { const bf16x8 vf = VFRAG(vb, (32 + 16 * s2) * DV_STR + 64 * dt, DV_STR); O[dt] = MFMA32(vf, pf, O[dt]); } }
;             }
;             __builtin_amdgcn_s_setprio(0);
.LBB0_305:
	v_exp_f32_e32 v80, v80
	v_exp_f32_e32 v81, v81
	v_exp_f32_e32 v82, v82
	v_exp_f32_e32 v83, v83
	v_exp_f32_e32 v84, v84
	v_exp_f32_e32 v85, v85
	v_exp_f32_e32 v86, v86
	v_exp_f32_e32 v87, v87
	v_add_f32_e32 v236, v80, v82
	v_add_f32_e32 v237, v81, v83
	s_setprio 1
	v_cvt_pk_bf16_f32 v232, v80, v81
	v_cvt_pk_bf16_f32 v233, v82, v83
	v_cvt_pk_bf16_f32 v234, v84, v85
	v_cvt_pk_bf16_f32 v235, v86, v87
	v_add_f32_e32 v236, v236, v84
	v_add_f32_e32 v237, v237, v85
	v_add_f32_e32 v236, v236, v86
	v_add_f32_e32 v237, v237, v87
	v_mfma_f32_32x32x16_bf16 v[48:63], v[148:151], v[232:235], v[48:63]
	ds_read_b64_tr_b16 v[148:149], v222 offset:45056
	ds_read_b64_tr_b16 v[150:151], v222 offset:47616
	v_exp_f32_e32 v88, v88
	v_exp_f32_e32 v89, v89
	v_mfma_f32_32x32x16_bf16 v[32:47], v[144:147], v[232:235], v[32:47]
	ds_read_b64_tr_b16 v[144:145], v222 offset:45120
	ds_read_b64_tr_b16 v[146:147], v222 offset:47680
	v_exp_f32_e32 v90, v90
	v_exp_f32_e32 v91, v91
	v_add_f32_e32 v236, v236, v88
	v_add_f32_e32 v237, v237, v89
	v_cvt_pk_bf16_f32 v80, v88, v89
	v_mfma_f32_32x32x16_bf16 v[16:31], v[140:143], v[232:235], v[16:31]
	ds_read_b64_tr_b16 v[140:141], v222 offset:45184
	ds_read_b64_tr_b16 v[142:143], v222 offset:47744
	v_exp_f32_e32 v92, v92
	v_exp_f32_e32 v93, v93
	v_add_f32_e32 v236, v236, v90
	v_add_f32_e32 v237, v237, v91
	v_cvt_pk_bf16_f32 v81, v90, v91
	v_mfma_f32_32x32x16_bf16 v[0:15], v[136:139], v[232:235], v[0:15]
	ds_read_b64_tr_b16 v[136:137], v222 offset:45248
	ds_read_b64_tr_b16 v[138:139], v222 offset:47808
	v_exp_f32_e32 v94, v94
	v_exp_f32_e32 v95, v95
	v_add_f32_e32 v236, v236, v92
	v_add_f32_e32 v237, v237, v93
	v_cvt_pk_bf16_f32 v82, v92, v93
	v_cvt_pk_bf16_f32 v83, v94, v95
	v_add_f32_e32 v236, v236, v94
	v_add_f32_e32 v237, v237, v95
	v_mfma_f32_32x32x16_bf16 v[48:63], v[128:131], v[80:83], v[48:63]
	ds_read_b64_tr_b16 v[128:129], v222 offset:50176
	ds_read_b64_tr_b16 v[130:131], v222 offset:52736
	v_exp_f32_e32 v64, v64
	v_exp_f32_e32 v65, v65
	v_mfma_f32_32x32x16_bf16 v[32:47], v[132:135], v[80:83], v[32:47]
	ds_read_b64_tr_b16 v[132:133], v222 offset:50240
	ds_read_b64_tr_b16 v[134:135], v222 offset:52800
	v_exp_f32_e32 v66, v66
	v_exp_f32_e32 v67, v67
	v_add_f32_e32 v236, v236, v64
	v_add_f32_e32 v237, v237, v65
	v_cvt_pk_bf16_f32 v84, v64, v65
	s_waitcnt lgkmcnt(14)
	v_mfma_f32_32x32x16_bf16 v[16:31], v[224:227], v[80:83], v[16:31]
	ds_read_b64_tr_b16 v[224:225], v222 offset:50304
	ds_read_b64_tr_b16 v[226:227], v222 offset:52864
	v_exp_f32_e32 v68, v68
	v_exp_f32_e32 v69, v69
	v_add_f32_e32 v236, v236, v66
	v_add_f32_e32 v237, v237, v67
	v_cvt_pk_bf16_f32 v85, v66, v67
	s_waitcnt lgkmcnt(14)
	v_mfma_f32_32x32x16_bf16 v[0:15], v[228:231], v[80:83], v[0:15]
	ds_read_b64_tr_b16 v[228:229], v222 offset:50368
	ds_read_b64_tr_b16 v[230:231], v222 offset:52928
	v_exp_f32_e32 v70, v70
	v_exp_f32_e32 v71, v71
	v_add_f32_e32 v236, v236, v68
	v_add_f32_e32 v237, v237, v69
	v_cvt_pk_bf16_f32 v86, v68, v69
	v_cvt_pk_bf16_f32 v87, v70, v71
	v_add_f32_e32 v236, v236, v70
	v_add_f32_e32 v237, v237, v71
	s_waitcnt lgkmcnt(8)
	v_mfma_f32_32x32x16_bf16 v[48:63], v[148:151], v[84:87], v[48:63]
	v_exp_f32_e32 v72, v72
	v_exp_f32_e32 v73, v73
	v_mfma_f32_32x32x16_bf16 v[32:47], v[144:147], v[84:87], v[32:47]
	v_exp_f32_e32 v74, v74
	v_exp_f32_e32 v75, v75
	v_add_f32_e32 v236, v236, v72
	v_add_f32_e32 v237, v237, v73
	v_cvt_pk_bf16_f32 v232, v72, v73
	v_mfma_f32_32x32x16_bf16 v[16:31], v[140:143], v[84:87], v[16:31]
	v_exp_f32_e32 v76, v76
	v_exp_f32_e32 v77, v77
	v_add_f32_e32 v236, v236, v74
	v_add_f32_e32 v237, v237, v75
	v_cvt_pk_bf16_f32 v233, v74, v75
	v_mfma_f32_32x32x16_bf16 v[0:15], v[136:139], v[84:87], v[0:15]
	v_exp_f32_e32 v78, v78
	v_exp_f32_e32 v79, v79
	v_add_f32_e32 v236, v236, v76
	v_add_f32_e32 v237, v237, v77
	v_cvt_pk_bf16_f32 v234, v76, v77
	v_cvt_pk_bf16_f32 v235, v78, v79
	v_add_f32_e32 v236, v236, v78
	v_add_f32_e32 v237, v237, v79
	v_add_f32_e32 v223, v236, v237
	v_add_f32_e32 v158, v158, v223
	s_waitcnt lgkmcnt(0)
	v_mfma_f32_32x32x16_bf16 v[48:63], v[128:131], v[232:235], v[48:63]
	v_mfma_f32_32x32x16_bf16 v[32:47], v[132:135], v[232:235], v[32:47]
	v_mfma_f32_32x32x16_bf16 v[16:31], v[224:227], v[232:235], v[16:31]
	v_mfma_f32_32x32x16_bf16 v[0:15], v[228:231], v[232:235], v[0:15]
	s_setprio 0
	s_andn2_b64 vcc, exec, s[66:67]
	s_cbranch_vccnz .LBB0_296

; #define MFMA32(a, b, c) __builtin_amdgcn_mfma_f32_32x32x16_bf16((a), (b), (c), 0, 0, 0)
; #define VFRAG(ptr, off0, STR) ({ const s16x4 lo_ = vtr((ptr) + (off0)); const s16x4 hi_ = vtr((ptr) + (off0) + 8 * (STR)); (bf16x8){lo_[0], lo_[1], lo_[2], lo_[3], hi_[0], hi_[1], hi_[2], hi_[3]}; })
; __device__ __forceinline__ void diff_unit(const Frame& F, int b, int h, int qi, float lam, int dry) {
;     ...
;             float ps = 0.f;
; #pragma unroll
;             for (int r = 0; r < 16; ++r) { s0[r] = __builtin_amdgcn_exp2f(s0[r] * LOG2E - ms); ps += s0[r]; }
;             if (!meta) {
; #pragma unroll
;                 for (int r = 0; r < 16; ++r) { s1[r] = __builtin_amdgcn_exp2f(s1[r] * LOG2E - ms); ps += s1[r]; }
;             }
;             lsum += ps;
;             __builtin_amdgcn_s_setprio(1);
;             { const bf16x8 pf = pack_step(s0, 0);
;               O[0] = MFMA32(vpre0, pf, O[0]); O[1] = MFMA32(vpre1, pf, O[1]); O[2] = MFMA32(vpre2, pf, O[2]); O[3] = MFMA32(vpre3, pf, O[3]); }
;             if (!meta) {
;                 { const bf16x8 pf = pack_step(s0, 1);
;                   O[0] = MFMA32(vprf0, pf, O[0]); O[1] = MFMA32(vprf1, pf, O[1]);
; #pragma unroll
;                   for (int dt = 2; dt < 4; ++dt) { const bf16x8 vf = VFRAG(vb, 16 * DV_STR + 64 * dt, DV_STR); O[dt] = MFMA32(vf, pf, O[dt]); } }
; #pragma unroll
;                 for (int s2 = 0; s2 < 2; ++s2) { const bf16x8 pf = pack_step(s1, s2);
; #pragma unroll
;                     for (int dt = 0; dt < 4; ++dt) { const bf16x8 vf = VFRAG(vb, (32 + 16 * s2) * DV_STR + 64 * dt, DV_STR); O[dt] = MFMA32(vf, pf, O[dt]); } }
;             }
;             __builtin_amdgcn_s_setprio(0);
.LBB0_324:
	v_exp_f32_e32 v80, v80
	v_exp_f32_e32 v81, v81
	v_exp_f32_e32 v82, v82
	v_exp_f32_e32 v83, v83
	v_exp_f32_e32 v84, v84
	v_exp_f32_e32 v85, v85
	v_exp_f32_e32 v86, v86
	v_exp_f32_e32 v87, v87
	v_add_f32_e32 v202, v80, v82
	v_add_f32_e32 v203, v81, v83
	s_setprio 1
	v_cvt_pk_bf16_f32 v198, v80, v81
	v_cvt_pk_bf16_f32 v199, v82, v83
	v_cvt_pk_bf16_f32 v200, v84, v85
	v_cvt_pk_bf16_f32 v201, v86, v87
	v_add_f32_e32 v202, v202, v84
	v_add_f32_e32 v203, v203, v85
	v_add_f32_e32 v202, v202, v86
	v_add_f32_e32 v203, v203, v87
	v_mfma_f32_32x32x16_bf16 v[48:63], v[148:151], v[198:201], v[48:63]
	ds_read_b64_tr_b16 v[148:149], v188 offset:45056
	ds_read_b64_tr_b16 v[150:151], v188 offset:47616
	v_exp_f32_e32 v88, v88
	v_exp_f32_e32 v89, v89
	v_mfma_f32_32x32x16_bf16 v[32:47], v[144:147], v[198:201], v[32:47]
	ds_read_b64_tr_b16 v[144:145], v188 offset:45120
	ds_read_b64_tr_b16 v[146:147], v188 offset:47680
	v_exp_f32_e32 v90, v90
	v_exp_f32_e32 v91, v91
	v_add_f32_e32 v202, v202, v88
	v_add_f32_e32 v203, v203, v89
	v_cvt_pk_bf16_f32 v80, v88, v89
	v_mfma_f32_32x32x16_bf16 v[16:31], v[140:143], v[198:201], v[16:31]
	ds_read_b64_tr_b16 v[140:141], v188 offset:45184
	ds_read_b64_tr_b16 v[142:143], v188 offset:47744
	v_exp_f32_e32 v92, v92
	v_exp_f32_e32 v93, v93
	v_add_f32_e32 v202, v202, v90
	v_add_f32_e32 v203, v203, v91
	v_cvt_pk_bf16_f32 v81, v90, v91
	v_mfma_f32_32x32x16_bf16 v[0:15], v[136:139], v[198:201], v[0:15]
	ds_read_b64_tr_b16 v[136:137], v188 offset:45248
	ds_read_b64_tr_b16 v[138:139], v188 offset:47808
	v_exp_f32_e32 v94, v94
	v_exp_f32_e32 v95, v95
	v_add_f32_e32 v202, v202, v92
	v_add_f32_e32 v203, v203, v93
	v_cvt_pk_bf16_f32 v82, v92, v93
	v_cvt_pk_bf16_f32 v83, v94, v95
	v_add_f32_e32 v202, v202, v94
	v_add_f32_e32 v203, v203, v95
	v_mfma_f32_32x32x16_bf16 v[48:63], v[128:131], v[80:83], v[48:63]
	ds_read_b64_tr_b16 v[128:129], v188 offset:50176
	ds_read_b64_tr_b16 v[130:131], v188 offset:52736
	v_exp_f32_e32 v64, v64
	v_exp_f32_e32 v65, v65
	v_mfma_f32_32x32x16_bf16 v[32:47], v[132:135], v[80:83], v[32:47]
	ds_read_b64_tr_b16 v[132:133], v188 offset:50240
	ds_read_b64_tr_b16 v[134:135], v188 offset:52800
	v_exp_f32_e32 v66, v66
	v_exp_f32_e32 v67, v67
	v_add_f32_e32 v202, v202, v64
	v_add_f32_e32 v203, v203, v65
	v_cvt_pk_bf16_f32 v84, v64, v65
	s_waitcnt lgkmcnt(14)
	v_mfma_f32_32x32x16_bf16 v[16:31], v[190:193], v[80:83], v[16:31]
	ds_read_b64_tr_b16 v[190:191], v188 offset:50304
	ds_read_b64_tr_b16 v[192:193], v188 offset:52864
	v_exp_f32_e32 v68, v68
	v_exp_f32_e32 v69, v69
	v_add_f32_e32 v202, v202, v66
	v_add_f32_e32 v203, v203, v67
	v_cvt_pk_bf16_f32 v85, v66, v67
	s_waitcnt lgkmcnt(14)
	v_mfma_f32_32x32x16_bf16 v[0:15], v[194:197], v[80:83], v[0:15]
	ds_read_b64_tr_b16 v[194:195], v188 offset:50368
	ds_read_b64_tr_b16 v[196:197], v188 offset:52928
	v_exp_f32_e32 v70, v70
	v_exp_f32_e32 v71, v71
	v_add_f32_e32 v202, v202, v68
	v_add_f32_e32 v203, v203, v69
	v_cvt_pk_bf16_f32 v86, v68, v69
	v_cvt_pk_bf16_f32 v87, v70, v71
	v_add_f32_e32 v202, v202, v70
	v_add_f32_e32 v203, v203, v71
	s_waitcnt lgkmcnt(8)
	v_mfma_f32_32x32x16_bf16 v[48:63], v[148:151], v[84:87], v[48:63]
	v_exp_f32_e32 v72, v72
	v_exp_f32_e32 v73, v73
	v_mfma_f32_32x32x16_bf16 v[32:47], v[144:147], v[84:87], v[32:47]
	v_exp_f32_e32 v74, v74
	v_exp_f32_e32 v75, v75
	v_add_f32_e32 v202, v202, v72
	v_add_f32_e32 v203, v203, v73
	v_cvt_pk_bf16_f32 v198, v72, v73
	v_mfma_f32_32x32x16_bf16 v[16:31], v[140:143], v[84:87], v[16:31]
	v_exp_f32_e32 v76, v76
	v_exp_f32_e32 v77, v77
	v_add_f32_e32 v202, v202, v74
	v_add_f32_e32 v203, v203, v75
	v_cvt_pk_bf16_f32 v199, v74, v75
	v_mfma_f32_32x32x16_bf16 v[0:15], v[136:139], v[84:87], v[0:15]
	v_exp_f32_e32 v78, v78
	v_exp_f32_e32 v79, v79
	v_add_f32_e32 v202, v202, v76
	v_add_f32_e32 v203, v203, v77
	v_cvt_pk_bf16_f32 v200, v76, v77
	v_cvt_pk_bf16_f32 v201, v78, v79
	v_add_f32_e32 v202, v202, v78
	v_add_f32_e32 v203, v203, v79
	v_add_f32_e32 v189, v202, v203
	v_add_f32_e32 v153, v153, v189
	s_waitcnt lgkmcnt(0)
	v_mfma_f32_32x32x16_bf16 v[48:63], v[128:131], v[198:201], v[48:63]
	v_mfma_f32_32x32x16_bf16 v[32:47], v[132:135], v[198:201], v[32:47]
	v_mfma_f32_32x32x16_bf16 v[16:31], v[190:193], v[198:201], v[16:31]
	v_mfma_f32_32x32x16_bf16 v[0:15], v[194:197], v[198:201], v[0:15]
	s_setprio 0
	s_andn2_b64 vcc, exec, s[90:91]
	s_cbranch_vccnz .LBB0_315
